# as previous + nt (streaming) hint on the SwiGLU hidden stores of the gate/up epilogue
# baseline (speedup 1.0000x reference)
.LBB0_410:
	v_lshl_add_u32 v140, s50, 8, v146
	v_ashrrev_i32_e32 v141, 31, v140
	v_lshl_add_u64 v[142:143], v[140:141], 2, s[46:47]
	global_load_dword v228, v[142:143], off sc1
	global_load_dword v229, v[142:143], off offset:64 sc1
	global_load_dword v230, v[142:143], off offset:128 sc1
	global_load_dword v231, v[142:143], off offset:192 sc1
	global_load_dword v232, v[142:143], off offset:512 sc1
	global_load_dword v233, v[142:143], off offset:576 sc1
	global_load_dword v234, v[142:143], off offset:640 sc1
	global_load_dword v235, v[142:143], off offset:704 sc1
	v_lshl_or_b32 v144, s52, 7, v148
	v_ashrrev_i32_e32 v145, 31, v144
	s_andn2_b64 vcc, exec, s[4:5]
	s_waitcnt vmcnt(7)
	v_fmamk_f32 v141, v228, 0x3a800000, v178
	v_rsq_f32_e32 v150, v141
	s_nop 0
	v_pk_mul_f32 v[126:127], v[126:127], v[150:151] op_sel_hi:[1,0]
	v_pk_mul_f32 v[118:119], v[118:119], v[150:151] op_sel_hi:[1,0]
	v_mul_f32_e32 v141, 0xbfb8aa3b, v126
	v_pk_mul_f32 v[118:119], v[126:127], v[118:119]
	v_mul_f32_e32 v126, 0xbfb8aa3b, v127
	v_exp_f32_e32 v126, v126
	v_pk_mul_f32 v[120:121], v[120:121], v[150:151] op_sel_hi:[1,0]
	v_pk_mul_f32 v[122:123], v[122:123], v[150:151] op_sel_hi:[1,0]
	v_pk_mul_f32 v[114:115], v[114:115], v[150:151] op_sel_hi:[1,0]
	v_add_f32_e32 v126, 1.0, v126
	v_rcp_f32_e32 v153, v126
	v_pk_mul_f32 v[126:127], v[128:129], v[150:151] op_sel_hi:[1,0]
	v_pk_mul_f32 v[114:115], v[122:123], v[114:115]
	v_mul_f32_e32 v128, 0xbfb8aa3b, v126
	v_pk_mul_f32 v[120:121], v[126:127], v[120:121]
	v_mul_f32_e32 v126, 0xbfb8aa3b, v127
	v_exp_f32_e32 v126, v126
	v_exp_f32_e32 v141, v141
	v_pk_mul_f32 v[116:117], v[116:117], v[150:151] op_sel_hi:[1,0]
	v_exp_f32_e32 v128, v128
	v_add_f32_e32 v126, 1.0, v126
	v_rcp_f32_e32 v129, v126
	v_mul_f32_e32 v126, 0xbfb8aa3b, v122
	v_mul_f32_e32 v122, 0xbfb8aa3b, v123
	v_exp_f32_e32 v126, v126
	v_exp_f32_e32 v122, v122
	v_add_f32_e32 v141, 1.0, v141
	v_rcp_f32_e32 v152, v141
	v_add_f32_e32 v126, 1.0, v126
	v_add_f32_e32 v122, 1.0, v122
	v_rcp_f32_e32 v126, v126
	v_rcp_f32_e32 v127, v122
	v_add_f32_e32 v128, 1.0, v128
	v_rcp_f32_e32 v128, v128
	v_pk_mul_f32 v[118:119], v[118:119], v[152:153]
	v_pk_mul_f32 v[122:123], v[114:115], v[126:127]
	v_pk_mul_f32 v[114:115], v[124:125], v[150:151] op_sel_hi:[1,0]
	v_pk_mul_f32 v[120:121], v[120:121], v[128:129]
	v_mul_f32_e32 v124, 0xbfb8aa3b, v114
	v_pk_mul_f32 v[116:117], v[114:115], v[116:117]
	v_mul_f32_e32 v114, 0xbfb8aa3b, v115
	v_exp_f32_e32 v124, v124
	v_exp_f32_e32 v114, v114
	v_cvt_pk_bf16_f32 v115, v120, v121
	v_lshlrev_b64 v[120:121], 1, v[144:145]
	v_add_f32_e32 v124, 1.0, v124
	v_add_f32_e32 v114, 1.0, v114
	v_rcp_f32_e32 v124, v124
	v_rcp_f32_e32 v125, v114
	v_cvt_pk_bf16_f32 v114, v118, v119
	v_mov_b64_e32 v[118:119], s[44:45]
	v_pk_mul_f32 v[124:125], v[116:117], v[124:125]
	v_cvt_pk_bf16_f32 v116, v122, v123
	v_mad_i64_i32 v[122:123], s[50:51], v140, s39, v[118:119]
	v_cvt_pk_bf16_f32 v117, v124, v125
	v_lshl_add_u64 v[122:123], v[122:123], 0, v[120:121]
	global_store_dwordx4 v[122:123], v[114:117], off nt
	s_nop 0
	s_nop 0
	v_or_b32_e32 v115, 16, v140
	s_waitcnt vmcnt(7)
	v_fmamk_f32 v114, v229, 0x3a800000, v178
	v_rsq_f32_e32 v114, v114
	s_nop 0
	v_pk_mul_f32 v[110:111], v[110:111], v[114:115] op_sel_hi:[1,0]
	v_pk_mul_f32 v[102:103], v[102:103], v[114:115] op_sel_hi:[1,0]
	v_mul_f32_e32 v116, 0xbfb8aa3b, v110
	v_pk_mul_f32 v[102:103], v[110:111], v[102:103]
	v_mul_f32_e32 v110, 0xbfb8aa3b, v111
	v_exp_f32_e32 v110, v110
	v_pk_mul_f32 v[104:105], v[104:105], v[114:115] op_sel_hi:[1,0]
	v_pk_mul_f32 v[106:107], v[106:107], v[114:115] op_sel_hi:[1,0]
	v_pk_mul_f32 v[98:99], v[98:99], v[114:115] op_sel_hi:[1,0]
	v_add_f32_e32 v110, 1.0, v110
	v_rcp_f32_e32 v117, v110
	v_pk_mul_f32 v[110:111], v[112:113], v[114:115] op_sel_hi:[1,0]
	v_pk_mul_f32 v[98:99], v[106:107], v[98:99]
	v_mul_f32_e32 v112, 0xbfb8aa3b, v110
	v_pk_mul_f32 v[104:105], v[110:111], v[104:105]
	v_mul_f32_e32 v110, 0xbfb8aa3b, v111
	v_exp_f32_e32 v110, v110
	v_pk_mul_f32 v[100:101], v[100:101], v[114:115] op_sel_hi:[1,0]
	v_exp_f32_e32 v116, v116
	v_exp_f32_e32 v112, v112
	v_add_f32_e32 v110, 1.0, v110
	v_rcp_f32_e32 v113, v110
	v_mul_f32_e32 v110, 0xbfb8aa3b, v106
	v_mul_f32_e32 v106, 0xbfb8aa3b, v107
	v_exp_f32_e32 v110, v110
	v_exp_f32_e32 v106, v106
	v_add_f32_e32 v116, 1.0, v116
	v_rcp_f32_e32 v116, v116
	v_add_f32_e32 v110, 1.0, v110
	v_add_f32_e32 v106, 1.0, v106
	v_rcp_f32_e32 v110, v110
	v_rcp_f32_e32 v111, v106
	v_add_f32_e32 v112, 1.0, v112
	v_rcp_f32_e32 v112, v112
	v_pk_mul_f32 v[102:103], v[102:103], v[116:117]
	v_pk_mul_f32 v[106:107], v[98:99], v[110:111]
	v_pk_mul_f32 v[98:99], v[108:109], v[114:115] op_sel_hi:[1,0]
	v_pk_mul_f32 v[104:105], v[104:105], v[112:113]
	v_mul_f32_e32 v108, 0xbfb8aa3b, v98
	v_pk_mul_f32 v[100:101], v[98:99], v[100:101]
	v_mul_f32_e32 v98, 0xbfb8aa3b, v99
	v_exp_f32_e32 v108, v108
	v_exp_f32_e32 v98, v98
	v_cvt_pk_bf16_f32 v99, v104, v105
	v_add_f32_e32 v108, 1.0, v108
	v_add_f32_e32 v98, 1.0, v98
	v_rcp_f32_e32 v108, v108
	v_rcp_f32_e32 v109, v98
	v_cvt_pk_bf16_f32 v98, v102, v103
	v_mad_i64_i32 v[102:103], s[50:51], v115, s39, v[118:119]
	v_pk_mul_f32 v[108:109], v[100:101], v[108:109]
	v_cvt_pk_bf16_f32 v100, v106, v107
	v_cvt_pk_bf16_f32 v101, v108, v109
	v_lshl_add_u64 v[102:103], v[102:103], 0, v[120:121]
	global_store_dwordx4 v[102:103], v[98:101], off nt
	s_nop 0
	s_nop 0
	v_or_b32_e32 v99, 32, v140
	s_waitcnt vmcnt(7)
	v_fmamk_f32 v98, v230, 0x3a800000, v178
	v_rsq_f32_e32 v98, v98
	s_nop 0
	v_pk_mul_f32 v[94:95], v[94:95], v[98:99] op_sel_hi:[1,0]
	v_pk_mul_f32 v[86:87], v[86:87], v[98:99] op_sel_hi:[1,0]
	v_mul_f32_e32 v100, 0xbfb8aa3b, v94
	v_pk_mul_f32 v[86:87], v[94:95], v[86:87]
	v_mul_f32_e32 v94, 0xbfb8aa3b, v95
	v_exp_f32_e32 v94, v94
	v_pk_mul_f32 v[88:89], v[88:89], v[98:99] op_sel_hi:[1,0]
	v_pk_mul_f32 v[90:91], v[90:91], v[98:99] op_sel_hi:[1,0]
	v_pk_mul_f32 v[82:83], v[82:83], v[98:99] op_sel_hi:[1,0]
	v_add_f32_e32 v94, 1.0, v94
	v_rcp_f32_e32 v101, v94
	v_pk_mul_f32 v[94:95], v[96:97], v[98:99] op_sel_hi:[1,0]
	v_pk_mul_f32 v[82:83], v[90:91], v[82:83]
	v_mul_f32_e32 v96, 0xbfb8aa3b, v94
	v_pk_mul_f32 v[88:89], v[94:95], v[88:89]
	v_mul_f32_e32 v94, 0xbfb8aa3b, v95
	v_exp_f32_e32 v94, v94
	v_pk_mul_f32 v[84:85], v[84:85], v[98:99] op_sel_hi:[1,0]
	v_exp_f32_e32 v100, v100
	v_exp_f32_e32 v96, v96
	v_add_f32_e32 v94, 1.0, v94
	v_rcp_f32_e32 v97, v94
	v_mul_f32_e32 v94, 0xbfb8aa3b, v90
	v_mul_f32_e32 v90, 0xbfb8aa3b, v91
	v_exp_f32_e32 v94, v94
	v_exp_f32_e32 v90, v90
	v_add_f32_e32 v100, 1.0, v100
	v_rcp_f32_e32 v100, v100
	v_add_f32_e32 v94, 1.0, v94
	v_add_f32_e32 v90, 1.0, v90
	v_rcp_f32_e32 v94, v94
	v_rcp_f32_e32 v95, v90
	v_add_f32_e32 v96, 1.0, v96
	v_rcp_f32_e32 v96, v96
	v_pk_mul_f32 v[86:87], v[86:87], v[100:101]
	v_pk_mul_f32 v[90:91], v[82:83], v[94:95]
	v_pk_mul_f32 v[82:83], v[92:93], v[98:99] op_sel_hi:[1,0]
	v_pk_mul_f32 v[88:89], v[88:89], v[96:97]
	v_mul_f32_e32 v92, 0xbfb8aa3b, v82
	v_pk_mul_f32 v[84:85], v[82:83], v[84:85]
	v_mul_f32_e32 v82, 0xbfb8aa3b, v83
	v_exp_f32_e32 v92, v92
	v_exp_f32_e32 v82, v82
	v_cvt_pk_bf16_f32 v83, v88, v89
	v_add_f32_e32 v92, 1.0, v92
	v_add_f32_e32 v82, 1.0, v82
	v_rcp_f32_e32 v92, v92
	v_rcp_f32_e32 v93, v82
	v_cvt_pk_bf16_f32 v82, v86, v87
	v_mad_i64_i32 v[86:87], s[50:51], v99, s39, v[118:119]
	v_pk_mul_f32 v[92:93], v[84:85], v[92:93]
	v_cvt_pk_bf16_f32 v84, v90, v91
	v_cvt_pk_bf16_f32 v85, v92, v93
	v_lshl_add_u64 v[86:87], v[86:87], 0, v[120:121]
	global_store_dwordx4 v[86:87], v[82:85], off nt
	s_nop 0
	s_nop 0
	v_or_b32_e32 v83, 48, v140
	s_waitcnt vmcnt(7)
	v_fmamk_f32 v82, v231, 0x3a800000, v178
	v_rsq_f32_e32 v82, v82
	s_nop 0
	v_pk_mul_f32 v[76:77], v[76:77], v[82:83] op_sel_hi:[1,0]
	v_pk_mul_f32 v[68:69], v[68:69], v[82:83] op_sel_hi:[1,0]
	v_mul_f32_e32 v84, 0xbfb8aa3b, v76
	v_pk_mul_f32 v[68:69], v[76:77], v[68:69]
	v_mul_f32_e32 v76, 0xbfb8aa3b, v77
	v_exp_f32_e32 v76, v76
	v_pk_mul_f32 v[70:71], v[70:71], v[82:83] op_sel_hi:[1,0]
	v_pk_mul_f32 v[72:73], v[72:73], v[82:83] op_sel_hi:[1,0]
	v_pk_mul_f32 v[64:65], v[64:65], v[82:83] op_sel_hi:[1,0]
	v_add_f32_e32 v76, 1.0, v76
	v_rcp_f32_e32 v85, v76
	v_pk_mul_f32 v[76:77], v[78:79], v[82:83] op_sel_hi:[1,0]
	v_pk_mul_f32 v[64:65], v[72:73], v[64:65]
	v_mul_f32_e32 v78, 0xbfb8aa3b, v76
	v_pk_mul_f32 v[70:71], v[76:77], v[70:71]
	v_mul_f32_e32 v76, 0xbfb8aa3b, v77
	v_exp_f32_e32 v76, v76
	v_pk_mul_f32 v[66:67], v[66:67], v[82:83] op_sel_hi:[1,0]
	v_exp_f32_e32 v84, v84
	v_exp_f32_e32 v78, v78
	v_add_f32_e32 v76, 1.0, v76
	v_rcp_f32_e32 v79, v76
	v_mul_f32_e32 v76, 0xbfb8aa3b, v72
	v_mul_f32_e32 v72, 0xbfb8aa3b, v73
	v_exp_f32_e32 v76, v76
	v_exp_f32_e32 v72, v72
	v_add_f32_e32 v84, 1.0, v84
	v_rcp_f32_e32 v84, v84
	v_add_f32_e32 v76, 1.0, v76
	v_add_f32_e32 v72, 1.0, v72
	v_rcp_f32_e32 v76, v76
	v_rcp_f32_e32 v77, v72
	v_add_f32_e32 v78, 1.0, v78
	v_rcp_f32_e32 v78, v78
	v_pk_mul_f32 v[68:69], v[68:69], v[84:85]
	v_pk_mul_f32 v[72:73], v[64:65], v[76:77]
	v_pk_mul_f32 v[64:65], v[74:75], v[82:83] op_sel_hi:[1,0]
	v_pk_mul_f32 v[70:71], v[70:71], v[78:79]
	v_mul_f32_e32 v74, 0xbfb8aa3b, v64
	v_pk_mul_f32 v[66:67], v[64:65], v[66:67]
	v_mul_f32_e32 v64, 0xbfb8aa3b, v65
	v_exp_f32_e32 v74, v74
	v_exp_f32_e32 v64, v64
	v_cvt_pk_bf16_f32 v65, v70, v71
	v_add_f32_e32 v74, 1.0, v74
	v_add_f32_e32 v64, 1.0, v64
	v_rcp_f32_e32 v74, v74
	v_rcp_f32_e32 v75, v64
	v_cvt_pk_bf16_f32 v64, v68, v69
	v_mad_i64_i32 v[68:69], s[50:51], v83, s39, v[118:119]
	v_pk_mul_f32 v[74:75], v[66:67], v[74:75]
	v_cvt_pk_bf16_f32 v66, v72, v73
	v_cvt_pk_bf16_f32 v67, v74, v75
	v_lshl_add_u64 v[68:69], v[68:69], 0, v[120:121]
	global_store_dwordx4 v[68:69], v[64:67], off nt
	s_nop 0
	s_nop 0
	v_add_u32_e32 v65, 0x80, v140
	s_waitcnt vmcnt(7)
	v_fmamk_f32 v64, v232, 0x3a800000, v178
	v_rsq_f32_e32 v64, v64
	s_nop 0
	v_pk_mul_f32 v[60:61], v[60:61], v[64:65] op_sel_hi:[1,0]
	v_pk_mul_f32 v[52:53], v[52:53], v[64:65] op_sel_hi:[1,0]
	v_mul_f32_e32 v66, 0xbfb8aa3b, v60
	v_pk_mul_f32 v[52:53], v[60:61], v[52:53]
	v_mul_f32_e32 v60, 0xbfb8aa3b, v61
	v_exp_f32_e32 v60, v60
	v_pk_mul_f32 v[54:55], v[54:55], v[64:65] op_sel_hi:[1,0]
	v_pk_mul_f32 v[56:57], v[56:57], v[64:65] op_sel_hi:[1,0]
	v_pk_mul_f32 v[48:49], v[48:49], v[64:65] op_sel_hi:[1,0]
	v_add_f32_e32 v60, 1.0, v60
	v_rcp_f32_e32 v67, v60
	v_pk_mul_f32 v[60:61], v[62:63], v[64:65] op_sel_hi:[1,0]
	v_pk_mul_f32 v[48:49], v[56:57], v[48:49]
	v_mul_f32_e32 v62, 0xbfb8aa3b, v60
	v_pk_mul_f32 v[54:55], v[60:61], v[54:55]
	v_mul_f32_e32 v60, 0xbfb8aa3b, v61
	v_exp_f32_e32 v60, v60
	v_pk_mul_f32 v[50:51], v[50:51], v[64:65] op_sel_hi:[1,0]
	v_exp_f32_e32 v66, v66
	v_exp_f32_e32 v62, v62
	v_add_f32_e32 v60, 1.0, v60
	v_rcp_f32_e32 v63, v60
	v_mul_f32_e32 v60, 0xbfb8aa3b, v56
	v_mul_f32_e32 v56, 0xbfb8aa3b, v57
	v_exp_f32_e32 v60, v60
	v_exp_f32_e32 v56, v56
	v_add_f32_e32 v66, 1.0, v66
	v_rcp_f32_e32 v66, v66
	v_add_f32_e32 v60, 1.0, v60
	v_add_f32_e32 v56, 1.0, v56
	v_rcp_f32_e32 v60, v60
	v_rcp_f32_e32 v61, v56
	v_add_f32_e32 v62, 1.0, v62
	v_rcp_f32_e32 v62, v62
	v_pk_mul_f32 v[52:53], v[52:53], v[66:67]
	v_pk_mul_f32 v[56:57], v[48:49], v[60:61]
	v_pk_mul_f32 v[48:49], v[58:59], v[64:65] op_sel_hi:[1,0]
	v_pk_mul_f32 v[54:55], v[54:55], v[62:63]
	v_mul_f32_e32 v58, 0xbfb8aa3b, v48
	v_pk_mul_f32 v[50:51], v[48:49], v[50:51]
	v_mul_f32_e32 v48, 0xbfb8aa3b, v49
	v_exp_f32_e32 v58, v58
	v_exp_f32_e32 v48, v48
	v_cvt_pk_bf16_f32 v49, v54, v55
	v_add_f32_e32 v58, 1.0, v58
	v_add_f32_e32 v48, 1.0, v48
	v_rcp_f32_e32 v58, v58
	v_rcp_f32_e32 v59, v48
	v_cvt_pk_bf16_f32 v48, v52, v53
	v_mad_i64_i32 v[52:53], s[50:51], v65, s39, v[118:119]
	v_pk_mul_f32 v[58:59], v[50:51], v[58:59]
	v_cvt_pk_bf16_f32 v50, v56, v57
	v_cvt_pk_bf16_f32 v51, v58, v59
	v_lshl_add_u64 v[52:53], v[52:53], 0, v[120:121]
	global_store_dwordx4 v[52:53], v[48:51], off nt
	s_nop 0
	s_nop 0
	v_add_u32_e32 v49, 0x90, v140
	s_waitcnt vmcnt(7)
	v_fmamk_f32 v48, v233, 0x3a800000, v178
	v_rsq_f32_e32 v48, v48
	s_nop 0
	v_pk_mul_f32 v[44:45], v[44:45], v[48:49] op_sel_hi:[1,0]
	v_pk_mul_f32 v[36:37], v[36:37], v[48:49] op_sel_hi:[1,0]
	v_mul_f32_e32 v50, 0xbfb8aa3b, v44
	v_pk_mul_f32 v[36:37], v[44:45], v[36:37]
	v_mul_f32_e32 v44, 0xbfb8aa3b, v45
	v_exp_f32_e32 v44, v44
	v_pk_mul_f32 v[38:39], v[38:39], v[48:49] op_sel_hi:[1,0]
	v_pk_mul_f32 v[40:41], v[40:41], v[48:49] op_sel_hi:[1,0]
	v_pk_mul_f32 v[32:33], v[32:33], v[48:49] op_sel_hi:[1,0]
	v_add_f32_e32 v44, 1.0, v44
	v_rcp_f32_e32 v51, v44
	v_pk_mul_f32 v[44:45], v[46:47], v[48:49] op_sel_hi:[1,0]
	v_pk_mul_f32 v[32:33], v[40:41], v[32:33]
	v_mul_f32_e32 v46, 0xbfb8aa3b, v44
	v_pk_mul_f32 v[38:39], v[44:45], v[38:39]
	v_mul_f32_e32 v44, 0xbfb8aa3b, v45
	v_exp_f32_e32 v44, v44
	v_pk_mul_f32 v[34:35], v[34:35], v[48:49] op_sel_hi:[1,0]
	v_exp_f32_e32 v50, v50
	v_exp_f32_e32 v46, v46
	v_add_f32_e32 v44, 1.0, v44
	v_rcp_f32_e32 v47, v44
	v_mul_f32_e32 v44, 0xbfb8aa3b, v40
	v_mul_f32_e32 v40, 0xbfb8aa3b, v41
	v_exp_f32_e32 v44, v44
	v_exp_f32_e32 v40, v40
	v_add_f32_e32 v50, 1.0, v50
	v_rcp_f32_e32 v50, v50
	v_add_f32_e32 v44, 1.0, v44
	v_add_f32_e32 v40, 1.0, v40
	v_rcp_f32_e32 v44, v44
	v_rcp_f32_e32 v45, v40
	v_add_f32_e32 v46, 1.0, v46
	v_rcp_f32_e32 v46, v46
	v_pk_mul_f32 v[36:37], v[36:37], v[50:51]
	v_pk_mul_f32 v[40:41], v[32:33], v[44:45]
	v_pk_mul_f32 v[32:33], v[42:43], v[48:49] op_sel_hi:[1,0]
	v_pk_mul_f32 v[38:39], v[38:39], v[46:47]
	v_mul_f32_e32 v42, 0xbfb8aa3b, v32
	v_pk_mul_f32 v[34:35], v[32:33], v[34:35]
	v_mul_f32_e32 v32, 0xbfb8aa3b, v33
	v_exp_f32_e32 v42, v42
	v_exp_f32_e32 v32, v32
	v_cvt_pk_bf16_f32 v33, v38, v39
	v_add_f32_e32 v42, 1.0, v42
	v_add_f32_e32 v32, 1.0, v32
	v_rcp_f32_e32 v42, v42
	v_rcp_f32_e32 v43, v32
	v_cvt_pk_bf16_f32 v32, v36, v37
	v_mad_i64_i32 v[36:37], s[50:51], v49, s39, v[118:119]
	v_pk_mul_f32 v[42:43], v[34:35], v[42:43]
	v_cvt_pk_bf16_f32 v34, v40, v41
	v_cvt_pk_bf16_f32 v35, v42, v43
	v_lshl_add_u64 v[36:37], v[36:37], 0, v[120:121]
	global_store_dwordx4 v[36:37], v[32:35], off nt
	s_nop 0
	s_nop 0
	v_add_u32_e32 v33, 0xa0, v140
	s_waitcnt vmcnt(7)
	v_fmamk_f32 v32, v234, 0x3a800000, v178
	v_rsq_f32_e32 v32, v32
	s_nop 0
	v_pk_mul_f32 v[28:29], v[28:29], v[32:33] op_sel_hi:[1,0]
	v_pk_mul_f32 v[20:21], v[20:21], v[32:33] op_sel_hi:[1,0]
	v_mul_f32_e32 v34, 0xbfb8aa3b, v28
	v_pk_mul_f32 v[20:21], v[28:29], v[20:21]
	v_mul_f32_e32 v28, 0xbfb8aa3b, v29
	v_exp_f32_e32 v28, v28
	v_pk_mul_f32 v[22:23], v[22:23], v[32:33] op_sel_hi:[1,0]
	v_pk_mul_f32 v[24:25], v[24:25], v[32:33] op_sel_hi:[1,0]
	v_pk_mul_f32 v[16:17], v[16:17], v[32:33] op_sel_hi:[1,0]
	v_add_f32_e32 v28, 1.0, v28
	v_rcp_f32_e32 v35, v28
	v_pk_mul_f32 v[28:29], v[30:31], v[32:33] op_sel_hi:[1,0]
	v_pk_mul_f32 v[16:17], v[24:25], v[16:17]
	v_mul_f32_e32 v30, 0xbfb8aa3b, v28
	v_pk_mul_f32 v[22:23], v[28:29], v[22:23]
	v_mul_f32_e32 v28, 0xbfb8aa3b, v29
	v_exp_f32_e32 v28, v28
	v_pk_mul_f32 v[18:19], v[18:19], v[32:33] op_sel_hi:[1,0]
	v_exp_f32_e32 v34, v34
	v_exp_f32_e32 v30, v30
	v_add_f32_e32 v28, 1.0, v28
	v_rcp_f32_e32 v31, v28
	v_mul_f32_e32 v28, 0xbfb8aa3b, v24
	v_mul_f32_e32 v24, 0xbfb8aa3b, v25
	v_exp_f32_e32 v28, v28
	v_exp_f32_e32 v24, v24
	v_add_f32_e32 v34, 1.0, v34
	v_rcp_f32_e32 v34, v34
	v_add_f32_e32 v28, 1.0, v28
	v_add_f32_e32 v24, 1.0, v24
	v_rcp_f32_e32 v28, v28
	v_rcp_f32_e32 v29, v24
	v_add_f32_e32 v30, 1.0, v30
	v_rcp_f32_e32 v30, v30
	v_pk_mul_f32 v[20:21], v[20:21], v[34:35]
	v_pk_mul_f32 v[24:25], v[16:17], v[28:29]
	v_pk_mul_f32 v[16:17], v[26:27], v[32:33] op_sel_hi:[1,0]
	v_pk_mul_f32 v[22:23], v[22:23], v[30:31]
	v_mul_f32_e32 v26, 0xbfb8aa3b, v16
	v_pk_mul_f32 v[18:19], v[16:17], v[18:19]
	v_mul_f32_e32 v16, 0xbfb8aa3b, v17
	v_exp_f32_e32 v26, v26
	v_exp_f32_e32 v16, v16
	v_cvt_pk_bf16_f32 v17, v22, v23
	v_add_f32_e32 v26, 1.0, v26
	v_add_f32_e32 v16, 1.0, v16
	v_rcp_f32_e32 v26, v26
	v_rcp_f32_e32 v27, v16
	v_cvt_pk_bf16_f32 v16, v20, v21
	v_mad_i64_i32 v[20:21], s[50:51], v33, s39, v[118:119]
	v_pk_mul_f32 v[26:27], v[18:19], v[26:27]
	v_cvt_pk_bf16_f32 v18, v24, v25
	v_cvt_pk_bf16_f32 v19, v26, v27
	v_lshl_add_u64 v[20:21], v[20:21], 0, v[120:121]
	global_store_dwordx4 v[20:21], v[16:19], off nt
	s_nop 0
	s_nop 0
	v_add_u32_e32 v17, 0xb0, v140
	s_waitcnt vmcnt(7)
	v_fmamk_f32 v16, v235, 0x3a800000, v178
	v_rsq_f32_e32 v16, v16
	s_nop 0
	v_pk_mul_f32 v[12:13], v[12:13], v[16:17] op_sel_hi:[1,0]
	v_pk_mul_f32 v[4:5], v[4:5], v[16:17] op_sel_hi:[1,0]
	v_mul_f32_e32 v18, 0xbfb8aa3b, v12
	v_pk_mul_f32 v[4:5], v[12:13], v[4:5]
	v_mul_f32_e32 v12, 0xbfb8aa3b, v13
	v_exp_f32_e32 v12, v12
	v_pk_mul_f32 v[6:7], v[6:7], v[16:17] op_sel_hi:[1,0]
	v_pk_mul_f32 v[8:9], v[8:9], v[16:17] op_sel_hi:[1,0]
	v_pk_mul_f32 v[0:1], v[0:1], v[16:17] op_sel_hi:[1,0]
	v_add_f32_e32 v12, 1.0, v12
	v_rcp_f32_e32 v19, v12
	v_pk_mul_f32 v[12:13], v[14:15], v[16:17] op_sel_hi:[1,0]
	v_pk_mul_f32 v[0:1], v[8:9], v[0:1]
	v_mul_f32_e32 v14, 0xbfb8aa3b, v12
	v_pk_mul_f32 v[6:7], v[12:13], v[6:7]
	v_mul_f32_e32 v12, 0xbfb8aa3b, v13
	v_exp_f32_e32 v12, v12
	v_pk_mul_f32 v[2:3], v[2:3], v[16:17] op_sel_hi:[1,0]
	v_exp_f32_e32 v18, v18
	v_exp_f32_e32 v14, v14
	v_add_f32_e32 v12, 1.0, v12
	v_rcp_f32_e32 v15, v12
	v_mul_f32_e32 v12, 0xbfb8aa3b, v8
	v_mul_f32_e32 v8, 0xbfb8aa3b, v9
	v_exp_f32_e32 v12, v12
	v_exp_f32_e32 v8, v8
	v_add_f32_e32 v18, 1.0, v18
	v_rcp_f32_e32 v18, v18
	v_add_f32_e32 v12, 1.0, v12
	v_add_f32_e32 v8, 1.0, v8
	v_rcp_f32_e32 v12, v12
	v_rcp_f32_e32 v13, v8
	v_add_f32_e32 v14, 1.0, v14
	v_rcp_f32_e32 v14, v14
	v_pk_mul_f32 v[4:5], v[4:5], v[18:19]
	v_pk_mul_f32 v[8:9], v[0:1], v[12:13]
	v_pk_mul_f32 v[0:1], v[10:11], v[16:17] op_sel_hi:[1,0]
	v_pk_mul_f32 v[6:7], v[6:7], v[14:15]
	v_mul_f32_e32 v10, 0xbfb8aa3b, v0
	v_pk_mul_f32 v[2:3], v[0:1], v[2:3]
	v_mul_f32_e32 v0, 0xbfb8aa3b, v1
	v_exp_f32_e32 v10, v10
	v_exp_f32_e32 v0, v0
	v_cvt_pk_bf16_f32 v1, v6, v7
	v_add_f32_e32 v10, 1.0, v10
	v_add_f32_e32 v0, 1.0, v0
	v_rcp_f32_e32 v10, v10
	v_rcp_f32_e32 v11, v0
	v_cvt_pk_bf16_f32 v0, v4, v5
	v_mad_i64_i32 v[4:5], s[50:51], v17, s39, v[118:119]
	v_pk_mul_f32 v[10:11], v[2:3], v[10:11]
	v_cvt_pk_bf16_f32 v2, v8, v9
	v_cvt_pk_bf16_f32 v3, v10, v11
	v_lshl_add_u64 v[4:5], v[4:5], 0, v[120:121]
	s_mov_b64 s[50:51], -1
	global_store_dwordx4 v[4:5], v[0:3], off nt
	s_cbranch_vccnz .LBB0_392
	s_andn2_b64 vcc, exec, s[42:43]
	s_cbranch_vccnz .LBB0_391
	s_barrier
	s_branch .LBB0_391
